# P1/P4 GEMM loops: first K-step pair peeled with inline-zero accumulators (no per-tile accumulator zeroing)
# speedup vs baseline: 1.0113x; 1.0113x over previous
.LBB0_71:
	s_ashr_i32 s47, s46, 31
	s_lshl_b64 s[20:21], s[46:47], 19
	s_add_u32 s48, s54, s20
	s_addc_u32 s49, s55, s21
	s_and_b64 s[20:21], s[36:37], exec
	s_cselect_b32 s18, s49, s15
	s_cselect_b32 s39, s48, s14
	s_ashr_i32 s45, s44, 31
	s_lshl_b64 s[20:21], s[44:45], 19
	s_add_u32 s50, s52, s20
	s_addc_u32 s51, s53, s21
	s_and_b64 s[20:21], s[36:37], exec
	s_cselect_b32 s45, s51, s17
	s_cselect_b32 s47, s50, s16
	s_add_u32 s14, s14, 0x40080
	s_addc_u32 s15, s15, 0
	s_add_u32 s69, s16, 0x100
	s_addc_u32 s70, s17, 0
	s_mov_b32 s71, -2
	s_add_u32 s16, s14, 0xfffc0080
	s_addc_u32 s17, s15, -1
	s_add_i32 s72, 0, 0x10000
	s_cmp_eq_u32 s71, 12
	s_cselect_b32 s21, s18, s17
	s_cselect_b32 s20, s39, s16
	v_add_u32_e32 v2, s72, v157
	s_cselect_b32 s17, s45, s70
	s_cselect_b32 s16, s47, s69
	s_add_i32 s74, 0, 0x14000
	ds_read_b128 v[144:147], v2
	ds_read_b128 v[148:151], v2 offset:1024
	ds_read_b128 v[152:155], v2 offset:2048
	ds_read_b128 v[162:165], v2 offset:3072
	v_add_u32_e32 v2, s74, v157
	ds_read_b128 v[166:169], v2
	ds_read_b128 v[170:173], v2 offset:1024
	ds_read_b128 v[174:177], v2 offset:2048
	ds_read_b128 v[178:181], v2 offset:3072
	v_lshl_add_u64 v[190:191], s[14:15], 0, v[138:139]
	s_add_i32 m0, s43, 0xc000
	ds_read_b128 v[182:185], v160
	ds_read_b128 v[186:189], v160 offset:1024
	ds_read_b128 v[202:205], v160 offset:2048
	ds_read_b128 v[214:217], v160 offset:3072
	ds_read_b128 v[228:231], v160 offset:4096
	ds_read_b128 v[232:235], v160 offset:5120
	ds_read_b128 v[236:239], v160 offset:6144
	ds_read_b128 v[240:243], v160 offset:7168
	global_load_lds_dwordx4 v[190:191], off
	v_lshl_add_u64 v[190:191], s[14:15], 0, v[140:141]
	s_add_i32 m0, s43, 0xe000
	s_nop 0
	global_load_lds_dwordx4 v[190:191], off
	s_waitcnt vmcnt(8)
	s_waitcnt lgkmcnt(0)
	s_barrier
	s_setprio 1
	s_waitcnt lgkmcnt(0)
	v_mfma_f32_16x16x32_bf16 v[128:131], v[144:147], v[182:185], 0
	v_mfma_f32_16x16x32_bf16 v[124:127], v[152:155], v[182:185], 0
	v_mfma_f32_16x16x32_bf16 v[112:115], v[144:147], v[202:205], 0
	v_mfma_f32_16x16x32_bf16 v[108:111], v[152:155], v[202:205], 0
	v_mfma_f32_16x16x32_bf16 v[96:99], v[144:147], v[228:231], 0
	v_mfma_f32_16x16x32_bf16 v[92:95], v[152:155], v[228:231], 0
	v_mfma_f32_16x16x32_bf16 v[80:83], v[144:147], v[236:239], 0
	v_mfma_f32_16x16x32_bf16 v[76:79], v[152:155], v[236:239], 0
	v_mfma_f32_16x16x32_bf16 v[128:131], v[148:151], v[186:189], v[128:131]
	v_mfma_f32_16x16x32_bf16 v[124:127], v[162:165], v[186:189], v[124:127]
	v_mfma_f32_16x16x32_bf16 v[112:115], v[148:151], v[214:217], v[112:115]
	v_mfma_f32_16x16x32_bf16 v[108:111], v[162:165], v[214:217], v[108:111]
	v_mfma_f32_16x16x32_bf16 v[96:99], v[148:151], v[232:235], v[96:99]
	v_mfma_f32_16x16x32_bf16 v[92:95], v[162:165], v[232:235], v[92:95]
	v_mfma_f32_16x16x32_bf16 v[80:83], v[148:151], v[240:243], v[80:83]
	v_mfma_f32_16x16x32_bf16 v[76:79], v[162:165], v[240:243], v[76:79]
	s_setprio 0
	s_setprio 1
	v_mfma_f32_16x16x32_bf16 v[120:123], v[166:169], v[182:185], 0
	v_mfma_f32_16x16x32_bf16 v[116:119], v[174:177], v[182:185], 0
	v_mfma_f32_16x16x32_bf16 v[104:107], v[166:169], v[202:205], 0
	v_mfma_f32_16x16x32_bf16 v[100:103], v[174:177], v[202:205], 0
	v_mfma_f32_16x16x32_bf16 v[88:91], v[166:169], v[228:231], 0
	v_mfma_f32_16x16x32_bf16 v[84:87], v[174:177], v[228:231], 0
	v_mfma_f32_16x16x32_bf16 v[72:75], v[166:169], v[236:239], 0
	v_mfma_f32_16x16x32_bf16 v[68:71], v[174:177], v[236:239], 0
	v_mfma_f32_16x16x32_bf16 v[120:123], v[170:173], v[186:189], v[120:123]
	v_mfma_f32_16x16x32_bf16 v[116:119], v[178:181], v[186:189], v[116:119]
	v_mfma_f32_16x16x32_bf16 v[104:107], v[170:173], v[214:217], v[104:107]
	v_mfma_f32_16x16x32_bf16 v[100:103], v[178:181], v[214:217], v[100:103]
	v_mfma_f32_16x16x32_bf16 v[88:91], v[170:173], v[232:235], v[88:91]
	v_mfma_f32_16x16x32_bf16 v[84:87], v[178:181], v[232:235], v[84:87]
	v_mfma_f32_16x16x32_bf16 v[72:75], v[170:173], v[240:243], v[72:75]
	v_mfma_f32_16x16x32_bf16 v[68:71], v[178:181], v[240:243], v[68:71]
	s_setprio 0
	s_barrier
	s_add_i32 s72, s72, s29
	v_lshl_add_u64 v[190:191], s[16:17], 0, v[132:133]
	s_mov_b32 m0, s72
	ds_read_b128 v[182:185], v160 offset:16384
	ds_read_b128 v[186:189], v160 offset:17408
	ds_read_b128 v[202:205], v160 offset:18432
	ds_read_b128 v[214:217], v160 offset:19456
	ds_read_b128 v[228:231], v160 offset:20480
	ds_read_b128 v[232:235], v160 offset:21504
	ds_read_b128 v[236:239], v160 offset:22528
	ds_read_b128 v[240:243], v160 offset:23552
	global_load_lds_dwordx4 v[190:191], off
	s_add_i32 m0, s72, 0x2000
	s_add_u32 s72, s16, 0x40000
	v_lshl_add_u64 v[206:207], s[16:17], 0, v[136:137]
	s_addc_u32 s73, s17, 0
	s_add_i32 s74, s74, s29
	global_load_lds_dwordx4 v[206:207], off
	v_lshl_add_u64 v[224:225], s[72:73], 0, v[132:133]
	s_mov_b32 m0, s74
	v_lshl_add_u64 v[244:245], s[20:21], 0, v[134:135]
	global_load_lds_dwordx4 v[224:225], off
	v_lshl_add_u64 v[224:225], s[72:73], 0, v[136:137]
	s_add_i32 m0, s74, 0x2000
	s_nop 0
	global_load_lds_dwordx4 v[224:225], off
	v_lshl_add_u64 v[224:225], s[20:21], 0, v[0:1]
	s_mov_b32 m0, s43
	s_nop 0
	global_load_lds_dwordx4 v[224:225], off
	s_mov_b32 m0, s56
	s_nop 0
	global_load_lds_dwordx4 v[244:245], off
	s_waitcnt vmcnt(8)
	s_waitcnt lgkmcnt(0)
	s_barrier
	s_setprio 1
	s_waitcnt lgkmcnt(0)
	v_mfma_f32_16x16x32_bf16 v[64:67], v[144:147], v[182:185], 0
	v_mfma_f32_16x16x32_bf16 v[60:63], v[152:155], v[182:185], 0
	v_mfma_f32_16x16x32_bf16 v[52:55], v[144:147], v[202:205], 0
	v_mfma_f32_16x16x32_bf16 v[44:47], v[152:155], v[202:205], 0
	v_mfma_f32_16x16x32_bf16 v[36:39], v[144:147], v[228:231], 0
	v_mfma_f32_16x16x32_bf16 v[28:31], v[152:155], v[228:231], 0
	v_mfma_f32_16x16x32_bf16 v[20:23], v[144:147], v[236:239], 0
	v_mfma_f32_16x16x32_bf16 v[12:15], v[152:155], v[236:239], 0
	v_mfma_f32_16x16x32_bf16 v[64:67], v[148:151], v[186:189], v[64:67]
	v_mfma_f32_16x16x32_bf16 v[60:63], v[162:165], v[186:189], v[60:63]
	v_mfma_f32_16x16x32_bf16 v[52:55], v[148:151], v[214:217], v[52:55]
	v_mfma_f32_16x16x32_bf16 v[44:47], v[162:165], v[214:217], v[44:47]
	v_mfma_f32_16x16x32_bf16 v[36:39], v[148:151], v[232:235], v[36:39]
	v_mfma_f32_16x16x32_bf16 v[28:31], v[162:165], v[232:235], v[28:31]
	v_mfma_f32_16x16x32_bf16 v[20:23], v[148:151], v[240:243], v[20:23]
	v_mfma_f32_16x16x32_bf16 v[12:15], v[162:165], v[240:243], v[12:15]
	s_setprio 0
	s_setprio 1
	v_mfma_f32_16x16x32_bf16 v[56:59], v[166:169], v[182:185], 0
	v_mfma_f32_16x16x32_bf16 v[48:51], v[174:177], v[182:185], 0
	v_mfma_f32_16x16x32_bf16 v[40:43], v[166:169], v[202:205], 0
	v_mfma_f32_16x16x32_bf16 v[32:35], v[174:177], v[202:205], 0
	v_mfma_f32_16x16x32_bf16 v[24:27], v[166:169], v[228:231], 0
	v_mfma_f32_16x16x32_bf16 v[16:19], v[174:177], v[228:231], 0
	v_mfma_f32_16x16x32_bf16 v[8:11], v[166:169], v[236:239], 0
	v_mfma_f32_16x16x32_bf16 v[4:7], v[174:177], v[236:239], 0
	v_mfma_f32_16x16x32_bf16 v[56:59], v[170:173], v[186:189], v[56:59]
	v_mfma_f32_16x16x32_bf16 v[48:51], v[178:181], v[186:189], v[48:51]
	v_mfma_f32_16x16x32_bf16 v[40:43], v[170:173], v[214:217], v[40:43]
	v_mfma_f32_16x16x32_bf16 v[32:35], v[178:181], v[214:217], v[32:35]
	v_mfma_f32_16x16x32_bf16 v[24:27], v[170:173], v[232:235], v[24:27]
	v_mfma_f32_16x16x32_bf16 v[16:19], v[178:181], v[232:235], v[16:19]
	v_mfma_f32_16x16x32_bf16 v[8:11], v[170:173], v[240:243], v[8:11]
	v_mfma_f32_16x16x32_bf16 v[4:7], v[178:181], v[240:243], v[4:7]
	s_setprio 0
	s_barrier
	s_add_i32 s72, 0, 0x18000
	v_add_u32_e32 v2, s72, v157
	s_add_i32 s73, 0, 0x1c000
	ds_read_b128 v[144:147], v2
	ds_read_b128 v[148:151], v2 offset:1024
	ds_read_b128 v[152:155], v2 offset:2048
	ds_read_b128 v[162:165], v2 offset:3072
	v_add_u32_e32 v2, s73, v157
	ds_read_b128 v[166:169], v2
	ds_read_b128 v[170:173], v2 offset:1024
	ds_read_b128 v[174:177], v2 offset:2048
	ds_read_b128 v[178:181], v2 offset:3072
	s_add_u32 s20, s20, 0x40000
	s_addc_u32 s21, s21, 0
	s_mov_b32 m0, s57
	v_lshl_add_u64 v[246:247], s[20:21], 0, v[0:1]
	ds_read_b128 v[182:185], v160 offset:32768
	ds_read_b128 v[186:189], v160 offset:33792
	ds_read_b128 v[202:205], v160 offset:34816
	ds_read_b128 v[214:217], v160 offset:35840
	ds_read_b128 v[228:231], v160 offset:36864
	ds_read_b128 v[232:235], v160 offset:37888
	ds_read_b128 v[236:239], v160 offset:38912
	ds_read_b128 v[240:243], v160 offset:39936
	global_load_lds_dwordx4 v[246:247], off
	v_lshl_add_u64 v[246:247], s[20:21], 0, v[134:135]
	s_mov_b32 m0, s58
	s_nop 0
	global_load_lds_dwordx4 v[246:247], off
	s_waitcnt vmcnt(8)
	s_waitcnt lgkmcnt(0)
	s_barrier
	s_setprio 1
	s_waitcnt lgkmcnt(0)
	v_mfma_f32_16x16x32_bf16 v[128:131], v[144:147], v[182:185], v[128:131]
	v_mfma_f32_16x16x32_bf16 v[124:127], v[152:155], v[182:185], v[124:127]
	v_mfma_f32_16x16x32_bf16 v[112:115], v[144:147], v[202:205], v[112:115]
	v_mfma_f32_16x16x32_bf16 v[108:111], v[152:155], v[202:205], v[108:111]
	v_mfma_f32_16x16x32_bf16 v[96:99], v[144:147], v[228:231], v[96:99]
	v_mfma_f32_16x16x32_bf16 v[92:95], v[152:155], v[228:231], v[92:95]
	v_mfma_f32_16x16x32_bf16 v[80:83], v[144:147], v[236:239], v[80:83]
	v_mfma_f32_16x16x32_bf16 v[76:79], v[152:155], v[236:239], v[76:79]
	v_mfma_f32_16x16x32_bf16 v[128:131], v[148:151], v[186:189], v[128:131]
	v_mfma_f32_16x16x32_bf16 v[124:127], v[162:165], v[186:189], v[124:127]
	v_mfma_f32_16x16x32_bf16 v[112:115], v[148:151], v[214:217], v[112:115]
	v_mfma_f32_16x16x32_bf16 v[108:111], v[162:165], v[214:217], v[108:111]
	v_mfma_f32_16x16x32_bf16 v[96:99], v[148:151], v[232:235], v[96:99]
	v_mfma_f32_16x16x32_bf16 v[92:95], v[162:165], v[232:235], v[92:95]
	v_mfma_f32_16x16x32_bf16 v[80:83], v[148:151], v[240:243], v[80:83]
	v_mfma_f32_16x16x32_bf16 v[76:79], v[162:165], v[240:243], v[76:79]
	s_setprio 0
	s_setprio 1
	v_mfma_f32_16x16x32_bf16 v[120:123], v[166:169], v[182:185], v[120:123]
	v_mfma_f32_16x16x32_bf16 v[116:119], v[174:177], v[182:185], v[116:119]
	v_mfma_f32_16x16x32_bf16 v[104:107], v[166:169], v[202:205], v[104:107]
	v_mfma_f32_16x16x32_bf16 v[100:103], v[174:177], v[202:205], v[100:103]
	v_mfma_f32_16x16x32_bf16 v[88:91], v[166:169], v[228:231], v[88:91]
	v_mfma_f32_16x16x32_bf16 v[84:87], v[174:177], v[228:231], v[84:87]
	v_mfma_f32_16x16x32_bf16 v[72:75], v[166:169], v[236:239], v[72:75]
	v_mfma_f32_16x16x32_bf16 v[68:71], v[174:177], v[236:239], v[68:71]
	v_mfma_f32_16x16x32_bf16 v[120:123], v[170:173], v[186:189], v[120:123]
	v_mfma_f32_16x16x32_bf16 v[116:119], v[178:181], v[186:189], v[116:119]
	v_mfma_f32_16x16x32_bf16 v[104:107], v[170:173], v[214:217], v[104:107]
	v_mfma_f32_16x16x32_bf16 v[100:103], v[178:181], v[214:217], v[100:103]
	v_mfma_f32_16x16x32_bf16 v[88:91], v[170:173], v[232:235], v[88:91]
	v_mfma_f32_16x16x32_bf16 v[84:87], v[178:181], v[232:235], v[84:87]
	v_mfma_f32_16x16x32_bf16 v[72:75], v[170:173], v[240:243], v[72:75]
	v_mfma_f32_16x16x32_bf16 v[68:71], v[178:181], v[240:243], v[68:71]
	s_setprio 0
	s_barrier
	s_add_i32 s20, s72, s29
	v_lshl_add_u64 v[190:191], v[190:191], 0, s[22:23]
	s_mov_b32 m0, s20
	ds_read_b128 v[182:185], v160 offset:49152
	ds_read_b128 v[186:189], v160 offset:50176
	ds_read_b128 v[202:205], v160 offset:51200
	ds_read_b128 v[214:217], v160 offset:52224
	ds_read_b128 v[228:231], v160 offset:53248
	ds_read_b128 v[232:235], v160 offset:54272
	ds_read_b128 v[236:239], v160 offset:55296
	ds_read_b128 v[240:243], v160 offset:56320
	global_load_lds_dwordx4 v[190:191], off
	s_add_i32 m0, s20, 0x2000
	s_add_u32 s16, s16, 0x40080
	v_lshl_add_u64 v[190:191], v[206:207], 0, s[22:23]
	s_addc_u32 s17, s17, 0
	s_add_i32 s20, s73, s29
	global_load_lds_dwordx4 v[190:191], off
	v_lshl_add_u64 v[190:191], s[16:17], 0, v[132:133]
	s_mov_b32 m0, s20
	s_nop 0
	global_load_lds_dwordx4 v[190:191], off
	v_lshl_add_u64 v[190:191], s[16:17], 0, v[136:137]
	s_add_i32 m0, s20, 0x2000
	s_nop 0
	global_load_lds_dwordx4 v[190:191], off
	v_lshl_add_u64 v[190:191], v[224:225], 0, s[22:23]
	s_mov_b32 m0, s60
	s_nop 0
	global_load_lds_dwordx4 v[190:191], off
	v_lshl_add_u64 v[190:191], v[244:245], 0, s[22:23]
	s_mov_b32 m0, s61
	s_nop 0
	global_load_lds_dwordx4 v[190:191], off
	s_waitcnt vmcnt(8)
	s_waitcnt lgkmcnt(0)
	s_barrier
	s_setprio 1
	s_waitcnt lgkmcnt(0)
	v_mfma_f32_16x16x32_bf16 v[64:67], v[144:147], v[182:185], v[64:67]
	v_mfma_f32_16x16x32_bf16 v[60:63], v[152:155], v[182:185], v[60:63]
	v_mfma_f32_16x16x32_bf16 v[52:55], v[144:147], v[202:205], v[52:55]
	v_mfma_f32_16x16x32_bf16 v[44:47], v[152:155], v[202:205], v[44:47]
	v_mfma_f32_16x16x32_bf16 v[36:39], v[144:147], v[228:231], v[36:39]
	v_mfma_f32_16x16x32_bf16 v[28:31], v[152:155], v[228:231], v[28:31]
	v_mfma_f32_16x16x32_bf16 v[20:23], v[144:147], v[236:239], v[20:23]
	v_mfma_f32_16x16x32_bf16 v[12:15], v[152:155], v[236:239], v[12:15]
	v_mfma_f32_16x16x32_bf16 v[64:67], v[148:151], v[186:189], v[64:67]
	v_mfma_f32_16x16x32_bf16 v[60:63], v[162:165], v[186:189], v[60:63]
	v_mfma_f32_16x16x32_bf16 v[52:55], v[148:151], v[214:217], v[52:55]
	v_mfma_f32_16x16x32_bf16 v[44:47], v[162:165], v[214:217], v[44:47]
	v_mfma_f32_16x16x32_bf16 v[36:39], v[148:151], v[232:235], v[36:39]
	v_mfma_f32_16x16x32_bf16 v[28:31], v[162:165], v[232:235], v[28:31]
	v_mfma_f32_16x16x32_bf16 v[20:23], v[148:151], v[240:243], v[20:23]
	v_mfma_f32_16x16x32_bf16 v[12:15], v[162:165], v[240:243], v[12:15]
	s_setprio 0
	s_setprio 1
	v_mfma_f32_16x16x32_bf16 v[56:59], v[166:169], v[182:185], v[56:59]
	v_mfma_f32_16x16x32_bf16 v[48:51], v[174:177], v[182:185], v[48:51]
	v_mfma_f32_16x16x32_bf16 v[40:43], v[166:169], v[202:205], v[40:43]
	v_mfma_f32_16x16x32_bf16 v[32:35], v[174:177], v[202:205], v[32:35]
	v_mfma_f32_16x16x32_bf16 v[24:27], v[166:169], v[228:231], v[24:27]
	v_mfma_f32_16x16x32_bf16 v[16:19], v[174:177], v[228:231], v[16:19]
	v_mfma_f32_16x16x32_bf16 v[8:11], v[166:169], v[236:239], v[8:11]
	v_mfma_f32_16x16x32_bf16 v[4:7], v[174:177], v[236:239], v[4:7]
	v_mfma_f32_16x16x32_bf16 v[56:59], v[170:173], v[186:189], v[56:59]
	v_mfma_f32_16x16x32_bf16 v[48:51], v[178:181], v[186:189], v[48:51]
	v_mfma_f32_16x16x32_bf16 v[40:43], v[170:173], v[214:217], v[40:43]
	v_mfma_f32_16x16x32_bf16 v[32:35], v[178:181], v[214:217], v[32:35]
	v_mfma_f32_16x16x32_bf16 v[24:27], v[170:173], v[232:235], v[24:27]
	v_mfma_f32_16x16x32_bf16 v[16:19], v[178:181], v[232:235], v[16:19]
	v_mfma_f32_16x16x32_bf16 v[8:11], v[170:173], v[240:243], v[8:11]
	v_mfma_f32_16x16x32_bf16 v[4:7], v[178:181], v[240:243], v[4:7]
	s_setprio 0
	s_barrier
	s_add_i32 s71, s71, 2
	s_add_u32 s14, s14, 0x100
	s_addc_u32 s15, s15, 0
	s_add_u32 s69, s69, 0x100
	s_addc_u32 s70, s70, 0
	s_cmp_gt_u32 s71, 13

.LBB0_532:
	s_ashr_i32 s11, s10, 31
	s_lshl_b64 s[12:13], s[10:11], 19
	s_add_u32 s12, s30, s12
	s_addc_u32 s13, s31, s13
	s_and_b64 s[20:21], s[36:37], exec
	s_cselect_b32 s11, s13, s15
	s_cselect_b32 s54, s12, s14
	s_ashr_i32 s9, s8, 31
	s_lshl_b64 s[20:21], s[8:9], 19
	s_add_u32 s24, s38, s20
	s_addc_u32 s25, s39, s21
	s_and_b64 s[20:21], s[36:37], exec
	s_cselect_b32 s9, s25, s17
	s_cselect_b32 s55, s24, s16
	s_add_u32 s14, s14, 0x40080
	s_addc_u32 s15, s15, 0
	s_add_u32 s56, s16, 0x100
	s_addc_u32 s57, s17, 0
	s_mov_b32 s58, -2
	s_add_u32 s16, s14, 0xfffc0080
	s_addc_u32 s17, s15, -1
	s_add_i32 s59, 0, 0x10000
	s_cmp_eq_u32 s58, 12
	s_cselect_b32 s21, s11, s17
	s_cselect_b32 s20, s54, s16
	s_cselect_b32 s17, s9, s57
	s_cselect_b32 s16, s55, s56
	s_add_i32 s62, 0, 0x14000
	v_add_u32_e32 v156, s59, v145
	v_add_u32_e32 v172, s62, v145
	ds_read_b128 v[140:143], v156
	ds_read_b128 v[148:151], v156 offset:1024
	ds_read_b128 v[152:155], v156 offset:2048
	ds_read_b128 v[156:159], v156 offset:3072
	ds_read_b128 v[160:163], v172
	ds_read_b128 v[164:167], v172 offset:1024
	ds_read_b128 v[168:171], v172 offset:2048
	ds_read_b128 v[172:175], v172 offset:3072
	v_lshl_add_u64 v[206:207], s[14:15], 0, v[136:137]
	s_add_i32 m0, s41, 0xc000
	ds_read_b128 v[176:179], v147
	ds_read_b128 v[180:183], v147 offset:1024
	ds_read_b128 v[184:187], v147 offset:2048
	ds_read_b128 v[188:191], v147 offset:3072
	ds_read_b128 v[202:205], v147 offset:4096
	ds_read_b128 v[214:217], v147 offset:5120
	ds_read_b128 v[228:231], v147 offset:6144
	ds_read_b128 v[232:235], v147 offset:7168
	global_load_lds_dwordx4 v[206:207], off
	v_lshl_add_u64 v[206:207], s[14:15], 0, v[138:139]
	s_add_i32 m0, s41, 0xe000
	s_nop 0
	global_load_lds_dwordx4 v[206:207], off
	s_waitcnt vmcnt(8)
	s_waitcnt lgkmcnt(0)
	s_barrier
	s_setprio 1
	s_waitcnt lgkmcnt(0)
	v_mfma_f32_16x16x32_bf16 v[128:131], v[140:143], v[176:179], 0
	v_mfma_f32_16x16x32_bf16 v[116:119], v[152:155], v[176:179], 0
	v_mfma_f32_16x16x32_bf16 v[112:115], v[140:143], v[184:187], 0
	v_mfma_f32_16x16x32_bf16 v[100:103], v[152:155], v[184:187], 0
	v_mfma_f32_16x16x32_bf16 v[96:99], v[140:143], v[202:205], 0
	v_mfma_f32_16x16x32_bf16 v[84:87], v[152:155], v[202:205], 0
	v_mfma_f32_16x16x32_bf16 v[80:83], v[140:143], v[228:231], 0
	v_mfma_f32_16x16x32_bf16 v[68:71], v[152:155], v[228:231], 0
	v_mfma_f32_16x16x32_bf16 v[128:131], v[148:151], v[180:183], v[128:131]
	v_mfma_f32_16x16x32_bf16 v[116:119], v[156:159], v[180:183], v[116:119]
	v_mfma_f32_16x16x32_bf16 v[112:115], v[148:151], v[188:191], v[112:115]
	v_mfma_f32_16x16x32_bf16 v[100:103], v[156:159], v[188:191], v[100:103]
	v_mfma_f32_16x16x32_bf16 v[96:99], v[148:151], v[214:217], v[96:99]
	v_mfma_f32_16x16x32_bf16 v[84:87], v[156:159], v[214:217], v[84:87]
	v_mfma_f32_16x16x32_bf16 v[80:83], v[148:151], v[232:235], v[80:83]
	v_mfma_f32_16x16x32_bf16 v[68:71], v[156:159], v[232:235], v[68:71]
	s_setprio 0
	s_setprio 1
	v_mfma_f32_16x16x32_bf16 v[124:127], v[160:163], v[176:179], 0
	v_mfma_f32_16x16x32_bf16 v[120:123], v[168:171], v[176:179], 0
	v_mfma_f32_16x16x32_bf16 v[108:111], v[160:163], v[184:187], 0
	v_mfma_f32_16x16x32_bf16 v[104:107], v[168:171], v[184:187], 0
	v_mfma_f32_16x16x32_bf16 v[92:95], v[160:163], v[202:205], 0
	v_mfma_f32_16x16x32_bf16 v[88:91], v[168:171], v[202:205], 0
	v_mfma_f32_16x16x32_bf16 v[76:79], v[160:163], v[228:231], 0
	v_mfma_f32_16x16x32_bf16 v[72:75], v[168:171], v[228:231], 0
	v_mfma_f32_16x16x32_bf16 v[124:127], v[164:167], v[180:183], v[124:127]
	v_mfma_f32_16x16x32_bf16 v[120:123], v[172:175], v[180:183], v[120:123]
	v_mfma_f32_16x16x32_bf16 v[108:111], v[164:167], v[188:191], v[108:111]
	v_mfma_f32_16x16x32_bf16 v[104:107], v[172:175], v[188:191], v[104:107]
	v_mfma_f32_16x16x32_bf16 v[92:95], v[164:167], v[214:217], v[92:95]
	v_mfma_f32_16x16x32_bf16 v[88:91], v[172:175], v[214:217], v[88:91]
	v_mfma_f32_16x16x32_bf16 v[76:79], v[164:167], v[232:235], v[76:79]
	v_mfma_f32_16x16x32_bf16 v[72:75], v[172:175], v[232:235], v[72:75]
	s_setprio 0
	s_barrier
	s_add_i32 s59, s59, s40
	v_lshl_add_u64 v[206:207], s[16:17], 0, v[2:3]
	s_mov_b32 m0, s59
	ds_read_b128 v[176:179], v147 offset:16384
	ds_read_b128 v[180:183], v147 offset:17408
	ds_read_b128 v[184:187], v147 offset:18432
	ds_read_b128 v[188:191], v147 offset:19456
	ds_read_b128 v[202:205], v147 offset:20480
	ds_read_b128 v[214:217], v147 offset:21504
	ds_read_b128 v[228:231], v147 offset:22528
	ds_read_b128 v[232:235], v147 offset:23552
	global_load_lds_dwordx4 v[206:207], off
	s_add_i32 m0, s59, 0x2000
	s_add_u32 s60, s16, 0x40000
	v_lshl_add_u64 v[224:225], s[16:17], 0, v[0:1]
	s_addc_u32 s61, s17, 0
	s_add_i32 s59, s62, s40
	global_load_lds_dwordx4 v[224:225], off
	v_lshl_add_u64 v[236:237], s[60:61], 0, v[2:3]
	s_mov_b32 m0, s59
	v_lshl_add_u64 v[238:239], s[20:21], 0, v[132:133]
	global_load_lds_dwordx4 v[236:237], off
	v_lshl_add_u64 v[236:237], s[60:61], 0, v[0:1]
	s_add_i32 m0, s59, 0x2000
	s_nop 0
	global_load_lds_dwordx4 v[236:237], off
	v_lshl_add_u64 v[236:237], s[20:21], 0, v[134:135]
	s_mov_b32 m0, s41
	s_nop 0
	global_load_lds_dwordx4 v[236:237], off
	s_mov_b32 m0, s46
	s_nop 0
	global_load_lds_dwordx4 v[238:239], off
	s_waitcnt vmcnt(8)
	s_waitcnt lgkmcnt(0)
	s_barrier
	s_setprio 1
	s_waitcnt lgkmcnt(0)
	v_mfma_f32_16x16x32_bf16 v[64:67], v[140:143], v[176:179], 0
	v_mfma_f32_16x16x32_bf16 v[52:55], v[152:155], v[176:179], 0
	v_mfma_f32_16x16x32_bf16 v[48:51], v[140:143], v[184:187], 0
	v_mfma_f32_16x16x32_bf16 v[36:39], v[152:155], v[184:187], 0
	v_mfma_f32_16x16x32_bf16 v[32:35], v[140:143], v[202:205], 0
	v_mfma_f32_16x16x32_bf16 v[20:23], v[152:155], v[202:205], 0
	v_mfma_f32_16x16x32_bf16 v[16:19], v[140:143], v[228:231], 0
	v_mfma_f32_16x16x32_bf16 v[8:11], v[152:155], v[228:231], 0
	v_mfma_f32_16x16x32_bf16 v[64:67], v[148:151], v[180:183], v[64:67]
	v_mfma_f32_16x16x32_bf16 v[52:55], v[156:159], v[180:183], v[52:55]
	v_mfma_f32_16x16x32_bf16 v[48:51], v[148:151], v[188:191], v[48:51]
	v_mfma_f32_16x16x32_bf16 v[36:39], v[156:159], v[188:191], v[36:39]
	v_mfma_f32_16x16x32_bf16 v[32:35], v[148:151], v[214:217], v[32:35]
	v_mfma_f32_16x16x32_bf16 v[20:23], v[156:159], v[214:217], v[20:23]
	v_mfma_f32_16x16x32_bf16 v[16:19], v[148:151], v[232:235], v[16:19]
	v_mfma_f32_16x16x32_bf16 v[8:11], v[156:159], v[232:235], v[8:11]
	s_setprio 0
	s_setprio 1
	v_mfma_f32_16x16x32_bf16 v[60:63], v[160:163], v[176:179], 0
	v_mfma_f32_16x16x32_bf16 v[56:59], v[168:171], v[176:179], 0
	v_mfma_f32_16x16x32_bf16 v[44:47], v[160:163], v[184:187], 0
	v_mfma_f32_16x16x32_bf16 v[40:43], v[168:171], v[184:187], 0
	v_mfma_f32_16x16x32_bf16 v[28:31], v[160:163], v[202:205], 0
	v_mfma_f32_16x16x32_bf16 v[24:27], v[168:171], v[202:205], 0
	v_mfma_f32_16x16x32_bf16 v[12:15], v[160:163], v[228:231], 0
	v_mfma_f32_16x16x32_bf16 v[4:7], v[168:171], v[228:231], 0
	v_mfma_f32_16x16x32_bf16 v[60:63], v[164:167], v[180:183], v[60:63]
	v_mfma_f32_16x16x32_bf16 v[56:59], v[172:175], v[180:183], v[56:59]
	v_mfma_f32_16x16x32_bf16 v[44:47], v[164:167], v[188:191], v[44:47]
	v_mfma_f32_16x16x32_bf16 v[40:43], v[172:175], v[188:191], v[40:43]
	v_mfma_f32_16x16x32_bf16 v[28:31], v[164:167], v[214:217], v[28:31]
	v_mfma_f32_16x16x32_bf16 v[24:27], v[172:175], v[214:217], v[24:27]
	v_mfma_f32_16x16x32_bf16 v[12:15], v[164:167], v[232:235], v[12:15]
	v_mfma_f32_16x16x32_bf16 v[4:7], v[172:175], v[232:235], v[4:7]
	s_setprio 0
	s_barrier
	s_add_i32 s59, 0, 0x18000
	s_add_i32 s60, 0, 0x1c000
	v_add_u32_e32 v156, s59, v145
	v_add_u32_e32 v172, s60, v145
	ds_read_b128 v[140:143], v156
	ds_read_b128 v[148:151], v156 offset:1024
	ds_read_b128 v[152:155], v156 offset:2048
	ds_read_b128 v[156:159], v156 offset:3072
	ds_read_b128 v[160:163], v172
	ds_read_b128 v[164:167], v172 offset:1024
	ds_read_b128 v[168:171], v172 offset:2048
	ds_read_b128 v[172:175], v172 offset:3072
	s_add_u32 s20, s20, 0x40000
	s_addc_u32 s21, s21, 0
	s_mov_b32 m0, s47
	v_lshl_add_u64 v[240:241], s[20:21], 0, v[134:135]
	ds_read_b128 v[176:179], v147 offset:32768
	ds_read_b128 v[180:183], v147 offset:33792
	ds_read_b128 v[184:187], v147 offset:34816
	ds_read_b128 v[188:191], v147 offset:35840
	ds_read_b128 v[202:205], v147 offset:36864
	ds_read_b128 v[214:217], v147 offset:37888
	ds_read_b128 v[228:231], v147 offset:38912
	ds_read_b128 v[232:235], v147 offset:39936
	global_load_lds_dwordx4 v[240:241], off
	v_lshl_add_u64 v[240:241], s[20:21], 0, v[132:133]
	s_mov_b32 m0, s48
	s_nop 0
	global_load_lds_dwordx4 v[240:241], off
	s_waitcnt vmcnt(8)
	s_waitcnt lgkmcnt(0)
	s_barrier
	s_setprio 1
	s_waitcnt lgkmcnt(0)
	v_mfma_f32_16x16x32_bf16 v[128:131], v[140:143], v[176:179], v[128:131]
	v_mfma_f32_16x16x32_bf16 v[116:119], v[152:155], v[176:179], v[116:119]
	v_mfma_f32_16x16x32_bf16 v[112:115], v[140:143], v[184:187], v[112:115]
	v_mfma_f32_16x16x32_bf16 v[100:103], v[152:155], v[184:187], v[100:103]
	v_mfma_f32_16x16x32_bf16 v[96:99], v[140:143], v[202:205], v[96:99]
	v_mfma_f32_16x16x32_bf16 v[84:87], v[152:155], v[202:205], v[84:87]
	v_mfma_f32_16x16x32_bf16 v[80:83], v[140:143], v[228:231], v[80:83]
	v_mfma_f32_16x16x32_bf16 v[68:71], v[152:155], v[228:231], v[68:71]
	v_mfma_f32_16x16x32_bf16 v[128:131], v[148:151], v[180:183], v[128:131]
	v_mfma_f32_16x16x32_bf16 v[116:119], v[156:159], v[180:183], v[116:119]
	v_mfma_f32_16x16x32_bf16 v[112:115], v[148:151], v[188:191], v[112:115]
	v_mfma_f32_16x16x32_bf16 v[100:103], v[156:159], v[188:191], v[100:103]
	v_mfma_f32_16x16x32_bf16 v[96:99], v[148:151], v[214:217], v[96:99]
	v_mfma_f32_16x16x32_bf16 v[84:87], v[156:159], v[214:217], v[84:87]
	v_mfma_f32_16x16x32_bf16 v[80:83], v[148:151], v[232:235], v[80:83]
	v_mfma_f32_16x16x32_bf16 v[68:71], v[156:159], v[232:235], v[68:71]
	s_setprio 0
	s_setprio 1
	v_mfma_f32_16x16x32_bf16 v[124:127], v[160:163], v[176:179], v[124:127]
	v_mfma_f32_16x16x32_bf16 v[120:123], v[168:171], v[176:179], v[120:123]
	v_mfma_f32_16x16x32_bf16 v[108:111], v[160:163], v[184:187], v[108:111]
	v_mfma_f32_16x16x32_bf16 v[104:107], v[168:171], v[184:187], v[104:107]
	v_mfma_f32_16x16x32_bf16 v[92:95], v[160:163], v[202:205], v[92:95]
	v_mfma_f32_16x16x32_bf16 v[88:91], v[168:171], v[202:205], v[88:91]
	v_mfma_f32_16x16x32_bf16 v[76:79], v[160:163], v[228:231], v[76:79]
	v_mfma_f32_16x16x32_bf16 v[72:75], v[168:171], v[228:231], v[72:75]
	v_mfma_f32_16x16x32_bf16 v[124:127], v[164:167], v[180:183], v[124:127]
	v_mfma_f32_16x16x32_bf16 v[120:123], v[172:175], v[180:183], v[120:123]
	v_mfma_f32_16x16x32_bf16 v[108:111], v[164:167], v[188:191], v[108:111]
	v_mfma_f32_16x16x32_bf16 v[104:107], v[172:175], v[188:191], v[104:107]
	v_mfma_f32_16x16x32_bf16 v[92:95], v[164:167], v[214:217], v[92:95]
	v_mfma_f32_16x16x32_bf16 v[88:91], v[172:175], v[214:217], v[88:91]
	v_mfma_f32_16x16x32_bf16 v[76:79], v[164:167], v[232:235], v[76:79]
	v_mfma_f32_16x16x32_bf16 v[72:75], v[172:175], v[232:235], v[72:75]
	s_setprio 0
	s_barrier
	s_add_i32 s20, s59, s40
	v_lshl_add_u64 v[206:207], v[206:207], 0, s[22:23]
	s_mov_b32 m0, s20
	ds_read_b128 v[176:179], v147 offset:49152
	ds_read_b128 v[180:183], v147 offset:50176
	ds_read_b128 v[184:187], v147 offset:51200
	ds_read_b128 v[188:191], v147 offset:52224
	ds_read_b128 v[202:205], v147 offset:53248
	ds_read_b128 v[214:217], v147 offset:54272
	ds_read_b128 v[228:231], v147 offset:55296
	ds_read_b128 v[232:235], v147 offset:56320
	global_load_lds_dwordx4 v[206:207], off
	s_add_i32 m0, s20, 0x2000
	s_add_u32 s16, s16, 0x40080
	v_lshl_add_u64 v[206:207], v[224:225], 0, s[22:23]
	s_addc_u32 s17, s17, 0
	s_add_i32 s20, s60, s40
	global_load_lds_dwordx4 v[206:207], off
	v_lshl_add_u64 v[206:207], s[16:17], 0, v[2:3]
	s_mov_b32 m0, s20
	s_nop 0
	global_load_lds_dwordx4 v[206:207], off
	v_lshl_add_u64 v[206:207], s[16:17], 0, v[0:1]
	s_add_i32 m0, s20, 0x2000
	s_nop 0
	global_load_lds_dwordx4 v[206:207], off
	v_lshl_add_u64 v[206:207], v[236:237], 0, s[22:23]
	s_mov_b32 m0, s49
	s_nop 0
	global_load_lds_dwordx4 v[206:207], off
	v_lshl_add_u64 v[206:207], v[238:239], 0, s[22:23]
	s_mov_b32 m0, s50
	s_nop 0
	global_load_lds_dwordx4 v[206:207], off
	s_waitcnt vmcnt(8)
	s_waitcnt lgkmcnt(0)
	s_barrier
	s_setprio 1
	s_waitcnt lgkmcnt(0)
	v_mfma_f32_16x16x32_bf16 v[64:67], v[140:143], v[176:179], v[64:67]
	v_mfma_f32_16x16x32_bf16 v[52:55], v[152:155], v[176:179], v[52:55]
	v_mfma_f32_16x16x32_bf16 v[48:51], v[140:143], v[184:187], v[48:51]
	v_mfma_f32_16x16x32_bf16 v[36:39], v[152:155], v[184:187], v[36:39]
	v_mfma_f32_16x16x32_bf16 v[32:35], v[140:143], v[202:205], v[32:35]
	v_mfma_f32_16x16x32_bf16 v[20:23], v[152:155], v[202:205], v[20:23]
	v_mfma_f32_16x16x32_bf16 v[16:19], v[140:143], v[228:231], v[16:19]
	v_mfma_f32_16x16x32_bf16 v[8:11], v[152:155], v[228:231], v[8:11]
	v_mfma_f32_16x16x32_bf16 v[64:67], v[148:151], v[180:183], v[64:67]
	v_mfma_f32_16x16x32_bf16 v[52:55], v[156:159], v[180:183], v[52:55]
	v_mfma_f32_16x16x32_bf16 v[48:51], v[148:151], v[188:191], v[48:51]
	v_mfma_f32_16x16x32_bf16 v[36:39], v[156:159], v[188:191], v[36:39]
	v_mfma_f32_16x16x32_bf16 v[32:35], v[148:151], v[214:217], v[32:35]
	v_mfma_f32_16x16x32_bf16 v[20:23], v[156:159], v[214:217], v[20:23]
	v_mfma_f32_16x16x32_bf16 v[16:19], v[148:151], v[232:235], v[16:19]
	v_mfma_f32_16x16x32_bf16 v[8:11], v[156:159], v[232:235], v[8:11]
	s_setprio 0
	s_setprio 1
	v_mfma_f32_16x16x32_bf16 v[60:63], v[160:163], v[176:179], v[60:63]
	v_mfma_f32_16x16x32_bf16 v[56:59], v[168:171], v[176:179], v[56:59]
	v_mfma_f32_16x16x32_bf16 v[44:47], v[160:163], v[184:187], v[44:47]
	v_mfma_f32_16x16x32_bf16 v[40:43], v[168:171], v[184:187], v[40:43]
	v_mfma_f32_16x16x32_bf16 v[28:31], v[160:163], v[202:205], v[28:31]
	v_mfma_f32_16x16x32_bf16 v[24:27], v[168:171], v[202:205], v[24:27]
	v_mfma_f32_16x16x32_bf16 v[12:15], v[160:163], v[228:231], v[12:15]
	v_mfma_f32_16x16x32_bf16 v[4:7], v[168:171], v[228:231], v[4:7]
	v_mfma_f32_16x16x32_bf16 v[60:63], v[164:167], v[180:183], v[60:63]
	v_mfma_f32_16x16x32_bf16 v[56:59], v[172:175], v[180:183], v[56:59]
	v_mfma_f32_16x16x32_bf16 v[44:47], v[164:167], v[188:191], v[44:47]
	v_mfma_f32_16x16x32_bf16 v[40:43], v[172:175], v[188:191], v[40:43]
	v_mfma_f32_16x16x32_bf16 v[28:31], v[164:167], v[214:217], v[28:31]
	v_mfma_f32_16x16x32_bf16 v[24:27], v[172:175], v[214:217], v[24:27]
	v_mfma_f32_16x16x32_bf16 v[12:15], v[164:167], v[232:235], v[12:15]
	v_mfma_f32_16x16x32_bf16 v[4:7], v[172:175], v[232:235], v[4:7]
	s_setprio 0
	s_barrier
	s_add_i32 s58, s58, 2
	s_add_u32 s14, s14, 0x100
	s_addc_u32 s15, s15, 0
	s_add_u32 s56, s56, 0x100
	s_addc_u32 s57, s57, 0
	s_cmp_gt_u32 s58, 13
